# g1 V^T tiles: bf16 transpose through LDS + 16-byte stores instead of 128 two-byte stores per lane
# baseline (speedup 1.0000x reference)
; DI u16 f2bf(float a) { return (u16)(pack2bf(a, 0.f) & 0xffffu); }
; DI void phase_g1(const Params& p, int layer, unsigned char* smem) {
;     ...
;     } else if (kind == 2) {
; #pragma unroll
;       for (int mi = 0; mi < 4; ++mi) {
;         int b = mrow[mi] / TP, t = mrow[mi] - b * TP;
; #pragma unroll
;         for (int ni = 0; ni < 8; ++ni)
; #pragma unroll
;           for (int r = 0; r < 4; ++r) {
;             int row = col0 + wn * 128 + ni * 16 + lg * 4 + r;
;             dst[((size_t)(b * vrows + row)) * TP + t] = f2bf(acc[ni][mi][r]);
;           }
;       }
.LBB0_1215:
	v_or_b32_e32 v136, 16, v130
	v_or_b32_e32 v4, 32, v130
	v_or_b32_e32 v2, 48, v130
	s_or_b64 s[2:3], s[2:3], s[52:53]
	v_ashrrev_i32_e32 v137, 31, v136
	v_ashrrev_i32_e32 v5, 31, v4
	v_ashrrev_i32_e32 v3, 31, v2
	s_andn2_b64 vcc, exec, s[2:3]
	s_mov_b64 s[2:3], -1
	s_cbranch_vccz .LBB0_1219
	s_andn2_b64 vcc, exec, s[50:51]
	s_cbranch_vccnz .LBB0_1218
	s_waitcnt lgkmcnt(0)
	s_barrier
	v_and_b32_e32 v2, 1, v166
	v_mul_u32_u24_e32 v3, 0x210, v174
	v_and_b32_e32 v4, -2, v173
	v_cmp_eq_u32_e32 vcc, 0, v2
	v_lshl_add_u32 v3, v4, 1, v3
	v_mul_u32_u24_e32 v4, 0x210, v2
	v_sub_u32_e32 v5, v130, v173
	v_add_u32_e32 v3, v3, v4
	v_cndmask_b32_e32 v136, v102, v103, vcc
	v_cndmask_b32_e32 v137, v104, v105, vcc
	v_cndmask_b32_e32 v138, v118, v119, vcc
	v_cndmask_b32_e32 v139, v120, v121, vcc
	v_mov_b32_dpp v140, v136 quad_perm:[1,0,3,2] row_mask:0xf bank_mask:0xf
	v_mov_b32_dpp v141, v137 quad_perm:[1,0,3,2] row_mask:0xf bank_mask:0xf
	v_mov_b32_dpp v142, v138 quad_perm:[1,0,3,2] row_mask:0xf bank_mask:0xf
	v_mov_b32_dpp v143, v139 quad_perm:[1,0,3,2] row_mask:0xf bank_mask:0xf
	v_cndmask_b32_e32 v144, v140, v102, vcc
	v_cndmask_b32_e32 v248, v103, v140, vcc
	v_cndmask_b32_e32 v225, v141, v104, vcc
	v_cndmask_b32_e32 v249, v105, v141, vcc
	v_cndmask_b32_e32 v242, v142, v118, vcc
	v_cndmask_b32_e32 v250, v119, v142, vcc
	v_cndmask_b32_e32 v243, v143, v120, vcc
	v_cndmask_b32_e32 v251, v121, v143, vcc
	v_cvt_pk_bf16_f32 v136, v144, v248
	v_cvt_pk_bf16_f32 v137, v225, v249
	v_cvt_pk_bf16_f32 v138, v242, v250
	v_cvt_pk_bf16_f32 v139, v243, v251
	ds_write_b32 v3, v136
	ds_write_b32 v3, v137 offset:1056
	ds_write_b32 v3, v138 offset:8448
	ds_write_b32 v3, v139 offset:9504
	v_cndmask_b32_e32 v136, v110, v111, vcc
	v_cndmask_b32_e32 v137, v112, v113, vcc
	v_cndmask_b32_e32 v138, v122, v123, vcc
	v_cndmask_b32_e32 v139, v124, v125, vcc
	v_mov_b32_dpp v140, v136 quad_perm:[1,0,3,2] row_mask:0xf bank_mask:0xf
	v_mov_b32_dpp v141, v137 quad_perm:[1,0,3,2] row_mask:0xf bank_mask:0xf
	v_mov_b32_dpp v142, v138 quad_perm:[1,0,3,2] row_mask:0xf bank_mask:0xf
	v_mov_b32_dpp v143, v139 quad_perm:[1,0,3,2] row_mask:0xf bank_mask:0xf
	v_cndmask_b32_e32 v144, v140, v110, vcc
	v_cndmask_b32_e32 v248, v111, v140, vcc
	v_cndmask_b32_e32 v225, v141, v112, vcc
	v_cndmask_b32_e32 v249, v113, v141, vcc
	v_cndmask_b32_e32 v242, v142, v122, vcc
	v_cndmask_b32_e32 v250, v123, v142, vcc
	v_cndmask_b32_e32 v243, v143, v124, vcc
	v_cndmask_b32_e32 v251, v125, v143, vcc
	v_cvt_pk_bf16_f32 v136, v144, v248
	v_cvt_pk_bf16_f32 v137, v225, v249
	v_cvt_pk_bf16_f32 v138, v242, v250
	v_cvt_pk_bf16_f32 v139, v243, v251
	ds_write_b32 v3, v136 offset:16896
	ds_write_b32 v3, v137 offset:17952
	ds_write_b32 v3, v138 offset:25344
	ds_write_b32 v3, v139 offset:26400
	v_cndmask_b32_e32 v136, v114, v115, vcc
	v_cndmask_b32_e32 v137, v116, v117, vcc
	v_cndmask_b32_e32 v138, v126, v127, vcc
	v_cndmask_b32_e32 v139, v128, v129, vcc
	v_mov_b32_dpp v140, v136 quad_perm:[1,0,3,2] row_mask:0xf bank_mask:0xf
	v_mov_b32_dpp v141, v137 quad_perm:[1,0,3,2] row_mask:0xf bank_mask:0xf
	v_mov_b32_dpp v142, v138 quad_perm:[1,0,3,2] row_mask:0xf bank_mask:0xf
	v_mov_b32_dpp v143, v139 quad_perm:[1,0,3,2] row_mask:0xf bank_mask:0xf
	v_cndmask_b32_e32 v144, v140, v114, vcc
	v_cndmask_b32_e32 v248, v115, v140, vcc
	v_cndmask_b32_e32 v225, v141, v116, vcc
	v_cndmask_b32_e32 v249, v117, v141, vcc
	v_cndmask_b32_e32 v242, v142, v126, vcc
	v_cndmask_b32_e32 v250, v127, v142, vcc
	v_cndmask_b32_e32 v243, v143, v128, vcc
	v_cndmask_b32_e32 v251, v129, v143, vcc
	v_cvt_pk_bf16_f32 v136, v144, v248
	v_cvt_pk_bf16_f32 v137, v225, v249
	v_cvt_pk_bf16_f32 v138, v242, v250
	v_cvt_pk_bf16_f32 v139, v243, v251
	ds_write_b32 v3, v136 offset:33792
	ds_write_b32 v3, v137 offset:34848
	ds_write_b32 v3, v138 offset:42240
	ds_write_b32 v3, v139 offset:43296
	v_cndmask_b32_e32 v136, v132, v133, vcc
	v_cndmask_b32_e32 v137, v100, v101, vcc
	v_cndmask_b32_e32 v138, v106, v107, vcc
	v_cndmask_b32_e32 v139, v98, v99, vcc
	v_mov_b32_dpp v140, v136 quad_perm:[1,0,3,2] row_mask:0xf bank_mask:0xf
	v_mov_b32_dpp v141, v137 quad_perm:[1,0,3,2] row_mask:0xf bank_mask:0xf
	v_mov_b32_dpp v142, v138 quad_perm:[1,0,3,2] row_mask:0xf bank_mask:0xf
	v_mov_b32_dpp v143, v139 quad_perm:[1,0,3,2] row_mask:0xf bank_mask:0xf
	v_cndmask_b32_e32 v144, v140, v132, vcc
	v_cndmask_b32_e32 v248, v133, v140, vcc
	v_cndmask_b32_e32 v225, v141, v100, vcc
	v_cndmask_b32_e32 v249, v101, v141, vcc
	v_cndmask_b32_e32 v242, v142, v106, vcc
	v_cndmask_b32_e32 v250, v107, v142, vcc
	v_cndmask_b32_e32 v243, v143, v98, vcc
	v_cndmask_b32_e32 v251, v99, v143, vcc
	v_cvt_pk_bf16_f32 v136, v144, v248
	v_cvt_pk_bf16_f32 v137, v225, v249
	v_cvt_pk_bf16_f32 v138, v242, v250
	v_cvt_pk_bf16_f32 v139, v243, v251
	ds_write_b32 v3, v136 offset:50688
	ds_write_b32 v3, v137 offset:51744
	ds_write_b32 v3, v138 offset:59136
	ds_write_b32 v3, v139 offset:60192
	v_cndmask_b32_e32 v136, v70, v71, vcc
	v_cndmask_b32_e32 v137, v72, v73, vcc
	v_cndmask_b32_e32 v138, v82, v83, vcc
	v_cndmask_b32_e32 v139, v84, v85, vcc
	v_mov_b32_dpp v140, v136 quad_perm:[1,0,3,2] row_mask:0xf bank_mask:0xf
	v_mov_b32_dpp v141, v137 quad_perm:[1,0,3,2] row_mask:0xf bank_mask:0xf
	v_mov_b32_dpp v142, v138 quad_perm:[1,0,3,2] row_mask:0xf bank_mask:0xf
	v_mov_b32_dpp v143, v139 quad_perm:[1,0,3,2] row_mask:0xf bank_mask:0xf
	v_cndmask_b32_e32 v144, v140, v70, vcc
	v_cndmask_b32_e32 v248, v71, v140, vcc
	v_cndmask_b32_e32 v225, v141, v72, vcc
	v_cndmask_b32_e32 v249, v73, v141, vcc
	v_cndmask_b32_e32 v242, v142, v82, vcc
	v_cndmask_b32_e32 v250, v83, v142, vcc
	v_cndmask_b32_e32 v243, v143, v84, vcc
; DI u16 f2bf(float a) { return (u16)(pack2bf(a, 0.f) & 0xffffu); }
; DI void phase_g1(const Params& p, int layer, unsigned char* smem) {
;     ...
;     } else if (kind == 2) {
; #pragma unroll
;       for (int mi = 0; mi < 4; ++mi) {
;         int b = mrow[mi] / TP, t = mrow[mi] - b * TP;
; #pragma unroll
;         for (int ni = 0; ni < 8; ++ni)
; #pragma unroll
;           for (int r = 0; r < 4; ++r) {
;             int row = col0 + wn * 128 + ni * 16 + lg * 4 + r;
;             dst[((size_t)(b * vrows + row)) * TP + t] = f2bf(acc[ni][mi][r]);
;           }
;       }
	v_cndmask_b32_e32 v251, v85, v143, vcc
	v_cvt_pk_bf16_f32 v136, v144, v248
	v_cvt_pk_bf16_f32 v137, v225, v249
	v_cvt_pk_bf16_f32 v138, v242, v250
	v_cvt_pk_bf16_f32 v139, v243, v251
	ds_write_b32 v3, v136 offset:32
	ds_write_b32 v3, v137 offset:1088
	ds_write_b32 v3, v138 offset:8480
	ds_write_b32 v3, v139 offset:9536
	v_cndmask_b32_e32 v136, v74, v75, vcc
	v_cndmask_b32_e32 v137, v76, v77, vcc
	v_cndmask_b32_e32 v138, v90, v91, vcc
	v_cndmask_b32_e32 v139, v92, v93, vcc
	v_mov_b32_dpp v140, v136 quad_perm:[1,0,3,2] row_mask:0xf bank_mask:0xf
	v_mov_b32_dpp v141, v137 quad_perm:[1,0,3,2] row_mask:0xf bank_mask:0xf
	v_mov_b32_dpp v142, v138 quad_perm:[1,0,3,2] row_mask:0xf bank_mask:0xf
	v_mov_b32_dpp v143, v139 quad_perm:[1,0,3,2] row_mask:0xf bank_mask:0xf
	v_cndmask_b32_e32 v144, v140, v74, vcc
	v_cndmask_b32_e32 v248, v75, v140, vcc
	v_cndmask_b32_e32 v225, v141, v76, vcc
	v_cndmask_b32_e32 v249, v77, v141, vcc
	v_cndmask_b32_e32 v242, v142, v90, vcc
	v_cndmask_b32_e32 v250, v91, v142, vcc
	v_cndmask_b32_e32 v243, v143, v92, vcc
	v_cndmask_b32_e32 v251, v93, v143, vcc
	v_cvt_pk_bf16_f32 v136, v144, v248
	v_cvt_pk_bf16_f32 v137, v225, v249
	v_cvt_pk_bf16_f32 v138, v242, v250
	v_cvt_pk_bf16_f32 v139, v243, v251
	ds_write_b32 v3, v136 offset:16928
	ds_write_b32 v3, v137 offset:17984
	ds_write_b32 v3, v138 offset:25376
	ds_write_b32 v3, v139 offset:26432
	v_cndmask_b32_e32 v136, v78, v79, vcc
	v_cndmask_b32_e32 v137, v80, v81, vcc
	v_cndmask_b32_e32 v138, v94, v95, vcc
	v_cndmask_b32_e32 v139, v96, v97, vcc
	v_mov_b32_dpp v140, v136 quad_perm:[1,0,3,2] row_mask:0xf bank_mask:0xf
	v_mov_b32_dpp v141, v137 quad_perm:[1,0,3,2] row_mask:0xf bank_mask:0xf
	v_mov_b32_dpp v142, v138 quad_perm:[1,0,3,2] row_mask:0xf bank_mask:0xf
	v_mov_b32_dpp v143, v139 quad_perm:[1,0,3,2] row_mask:0xf bank_mask:0xf
	v_cndmask_b32_e32 v144, v140, v78, vcc
	v_cndmask_b32_e32 v248, v79, v140, vcc
	v_cndmask_b32_e32 v225, v141, v80, vcc
	v_cndmask_b32_e32 v249, v81, v141, vcc
	v_cndmask_b32_e32 v242, v142, v94, vcc
	v_cndmask_b32_e32 v250, v95, v142, vcc
	v_cndmask_b32_e32 v243, v143, v96, vcc
	v_cndmask_b32_e32 v251, v97, v143, vcc
	v_cvt_pk_bf16_f32 v136, v144, v248
	v_cvt_pk_bf16_f32 v137, v225, v249
	v_cvt_pk_bf16_f32 v138, v242, v250
	v_cvt_pk_bf16_f32 v139, v243, v251
	ds_write_b32 v3, v136 offset:33824
	ds_write_b32 v3, v137 offset:34880
	ds_write_b32 v3, v138 offset:42272
	ds_write_b32 v3, v139 offset:43328
	v_cndmask_b32_e32 v136, v108, v109, vcc
	v_cndmask_b32_e32 v137, v68, v69, vcc
	v_cndmask_b32_e32 v138, v86, v87, vcc
	v_cndmask_b32_e32 v139, v66, v67, vcc
	v_mov_b32_dpp v140, v136 quad_perm:[1,0,3,2] row_mask:0xf bank_mask:0xf
	v_mov_b32_dpp v141, v137 quad_perm:[1,0,3,2] row_mask:0xf bank_mask:0xf
	v_mov_b32_dpp v142, v138 quad_perm:[1,0,3,2] row_mask:0xf bank_mask:0xf
	v_mov_b32_dpp v143, v139 quad_perm:[1,0,3,2] row_mask:0xf bank_mask:0xf
	v_cndmask_b32_e32 v144, v140, v108, vcc
	v_cndmask_b32_e32 v248, v109, v140, vcc
	v_cndmask_b32_e32 v225, v141, v68, vcc
	v_cndmask_b32_e32 v249, v69, v141, vcc
	v_cndmask_b32_e32 v242, v142, v86, vcc
	v_cndmask_b32_e32 v250, v87, v142, vcc
	v_cndmask_b32_e32 v243, v143, v66, vcc
	v_cndmask_b32_e32 v251, v67, v143, vcc
	v_cvt_pk_bf16_f32 v136, v144, v248
	v_cvt_pk_bf16_f32 v137, v225, v249
	v_cvt_pk_bf16_f32 v138, v242, v250
	v_cvt_pk_bf16_f32 v139, v243, v251
	ds_write_b32 v3, v136 offset:50720
	ds_write_b32 v3, v137 offset:51776
	ds_write_b32 v3, v138 offset:59168
	ds_write_b32 v3, v139 offset:60224
	v_cndmask_b32_e32 v136, v38, v39, vcc
	v_cndmask_b32_e32 v137, v40, v41, vcc
	v_cndmask_b32_e32 v138, v50, v51, vcc
	v_cndmask_b32_e32 v139, v52, v53, vcc
	v_mov_b32_dpp v140, v136 quad_perm:[1,0,3,2] row_mask:0xf bank_mask:0xf
	v_mov_b32_dpp v141, v137 quad_perm:[1,0,3,2] row_mask:0xf bank_mask:0xf
	v_mov_b32_dpp v142, v138 quad_perm:[1,0,3,2] row_mask:0xf bank_mask:0xf
	v_mov_b32_dpp v143, v139 quad_perm:[1,0,3,2] row_mask:0xf bank_mask:0xf
	v_cndmask_b32_e32 v144, v140, v38, vcc
	v_cndmask_b32_e32 v248, v39, v140, vcc
	v_cndmask_b32_e32 v225, v141, v40, vcc
	v_cndmask_b32_e32 v249, v41, v141, vcc
	v_cndmask_b32_e32 v242, v142, v50, vcc
	v_cndmask_b32_e32 v250, v51, v142, vcc
	v_cndmask_b32_e32 v243, v143, v52, vcc
	v_cndmask_b32_e32 v251, v53, v143, vcc
	v_cvt_pk_bf16_f32 v136, v144, v248
	v_cvt_pk_bf16_f32 v137, v225, v249
	v_cvt_pk_bf16_f32 v138, v242, v250
	v_cvt_pk_bf16_f32 v139, v243, v251
	ds_write_b32 v3, v136 offset:64
	ds_write_b32 v3, v137 offset:1120
	ds_write_b32 v3, v138 offset:8512
	ds_write_b32 v3, v139 offset:9568
	v_cndmask_b32_e32 v136, v42, v43, vcc
	v_cndmask_b32_e32 v137, v44, v45, vcc
	v_cndmask_b32_e32 v138, v54, v55, vcc
	v_cndmask_b32_e32 v139, v56, v57, vcc
	v_mov_b32_dpp v140, v136 quad_perm:[1,0,3,2] row_mask:0xf bank_mask:0xf
	v_mov_b32_dpp v141, v137 quad_perm:[1,0,3,2] row_mask:0xf bank_mask:0xf
	v_mov_b32_dpp v142, v138 quad_perm:[1,0,3,2] row_mask:0xf bank_mask:0xf
	v_mov_b32_dpp v143, v139 quad_perm:[1,0,3,2] row_mask:0xf bank_mask:0xf
	v_cndmask_b32_e32 v144, v140, v42, vcc
	v_cndmask_b32_e32 v248, v43, v140, vcc
	v_cndmask_b32_e32 v225, v141, v44, vcc
	v_cndmask_b32_e32 v249, v45, v141, vcc
	v_cndmask_b32_e32 v242, v142, v54, vcc
	v_cndmask_b32_e32 v250, v55, v142, vcc
	v_cndmask_b32_e32 v243, v143, v56, vcc
	v_cndmask_b32_e32 v251, v57, v143, vcc
	v_cvt_pk_bf16_f32 v136, v144, v248
	v_cvt_pk_bf16_f32 v137, v225, v249
	v_cvt_pk_bf16_f32 v138, v242, v250
	v_cvt_pk_bf16_f32 v139, v243, v251
	ds_write_b32 v3, v136 offset:16960
	ds_write_b32 v3, v137 offset:18016
	ds_write_b32 v3, v138 offset:25408
	ds_write_b32 v3, v139 offset:26464
	v_cndmask_b32_e32 v136, v46, v47, vcc
; DI u16 f2bf(float a) { return (u16)(pack2bf(a, 0.f) & 0xffffu); }
; DI void phase_g1(const Params& p, int layer, unsigned char* smem) {
;     ...
;     } else if (kind == 2) {
; #pragma unroll
;       for (int mi = 0; mi < 4; ++mi) {
;         int b = mrow[mi] / TP, t = mrow[mi] - b * TP;
; #pragma unroll
;         for (int ni = 0; ni < 8; ++ni)
; #pragma unroll
;           for (int r = 0; r < 4; ++r) {
;             int row = col0 + wn * 128 + ni * 16 + lg * 4 + r;
;             dst[((size_t)(b * vrows + row)) * TP + t] = f2bf(acc[ni][mi][r]);
;           }
;       }
	v_cndmask_b32_e32 v137, v48, v49, vcc
	v_cndmask_b32_e32 v138, v58, v59, vcc
	v_cndmask_b32_e32 v139, v60, v61, vcc
	v_mov_b32_dpp v140, v136 quad_perm:[1,0,3,2] row_mask:0xf bank_mask:0xf
	v_mov_b32_dpp v141, v137 quad_perm:[1,0,3,2] row_mask:0xf bank_mask:0xf
	v_mov_b32_dpp v142, v138 quad_perm:[1,0,3,2] row_mask:0xf bank_mask:0xf
	v_mov_b32_dpp v143, v139 quad_perm:[1,0,3,2] row_mask:0xf bank_mask:0xf
	v_cndmask_b32_e32 v144, v140, v46, vcc
	v_cndmask_b32_e32 v248, v47, v140, vcc
	v_cndmask_b32_e32 v225, v141, v48, vcc
	v_cndmask_b32_e32 v249, v49, v141, vcc
	v_cndmask_b32_e32 v242, v142, v58, vcc
	v_cndmask_b32_e32 v250, v59, v142, vcc
	v_cndmask_b32_e32 v243, v143, v60, vcc
	v_cndmask_b32_e32 v251, v61, v143, vcc
	v_cvt_pk_bf16_f32 v136, v144, v248
	v_cvt_pk_bf16_f32 v137, v225, v249
	v_cvt_pk_bf16_f32 v138, v242, v250
	v_cvt_pk_bf16_f32 v139, v243, v251
	ds_write_b32 v3, v136 offset:33856
	ds_write_b32 v3, v137 offset:34912
	ds_write_b32 v3, v138 offset:42304
	ds_write_b32 v3, v139 offset:43360
	v_cndmask_b32_e32 v136, v134, v135, vcc
	v_cndmask_b32_e32 v137, v36, v37, vcc
	v_cndmask_b32_e32 v138, v88, v89, vcc
	v_cndmask_b32_e32 v139, v64, v65, vcc
	v_mov_b32_dpp v140, v136 quad_perm:[1,0,3,2] row_mask:0xf bank_mask:0xf
	v_mov_b32_dpp v141, v137 quad_perm:[1,0,3,2] row_mask:0xf bank_mask:0xf
	v_mov_b32_dpp v142, v138 quad_perm:[1,0,3,2] row_mask:0xf bank_mask:0xf
	v_mov_b32_dpp v143, v139 quad_perm:[1,0,3,2] row_mask:0xf bank_mask:0xf
	v_cndmask_b32_e32 v144, v140, v134, vcc
	v_cndmask_b32_e32 v248, v135, v140, vcc
	v_cndmask_b32_e32 v225, v141, v36, vcc
	v_cndmask_b32_e32 v249, v37, v141, vcc
	v_cndmask_b32_e32 v242, v142, v88, vcc
	v_cndmask_b32_e32 v250, v89, v142, vcc
	v_cndmask_b32_e32 v243, v143, v64, vcc
	v_cndmask_b32_e32 v251, v65, v143, vcc
	v_cvt_pk_bf16_f32 v136, v144, v248
	v_cvt_pk_bf16_f32 v137, v225, v249
	v_cvt_pk_bf16_f32 v138, v242, v250
	v_cvt_pk_bf16_f32 v139, v243, v251
	ds_write_b32 v3, v136 offset:50752
	ds_write_b32 v3, v137 offset:51808
	ds_write_b32 v3, v138 offset:59200
	ds_write_b32 v3, v139 offset:60256
	v_cndmask_b32_e32 v136, v62, v63, vcc
	v_cndmask_b32_e32 v137, v34, v35, vcc
	v_cndmask_b32_e32 v138, v14, v15, vcc
	v_cndmask_b32_e32 v139, v16, v17, vcc
	v_mov_b32_dpp v140, v136 quad_perm:[1,0,3,2] row_mask:0xf bank_mask:0xf
	v_mov_b32_dpp v141, v137 quad_perm:[1,0,3,2] row_mask:0xf bank_mask:0xf
	v_mov_b32_dpp v142, v138 quad_perm:[1,0,3,2] row_mask:0xf bank_mask:0xf
	v_mov_b32_dpp v143, v139 quad_perm:[1,0,3,2] row_mask:0xf bank_mask:0xf
	v_cndmask_b32_e32 v144, v140, v62, vcc
	v_cndmask_b32_e32 v248, v63, v140, vcc
	v_cndmask_b32_e32 v225, v141, v34, vcc
	v_cndmask_b32_e32 v249, v35, v141, vcc
	v_cndmask_b32_e32 v242, v142, v14, vcc
	v_cndmask_b32_e32 v250, v15, v142, vcc
	v_cndmask_b32_e32 v243, v143, v16, vcc
	v_cndmask_b32_e32 v251, v17, v143, vcc
	v_cvt_pk_bf16_f32 v136, v144, v248
	v_cvt_pk_bf16_f32 v137, v225, v249
	v_cvt_pk_bf16_f32 v138, v242, v250
	v_cvt_pk_bf16_f32 v139, v243, v251
	ds_write_b32 v3, v136 offset:96
	ds_write_b32 v3, v137 offset:1152
	ds_write_b32 v3, v138 offset:8544
	ds_write_b32 v3, v139 offset:9600
	v_cndmask_b32_e32 v136, v6, v7, vcc
	v_cndmask_b32_e32 v137, v8, v9, vcc
	v_cndmask_b32_e32 v138, v22, v23, vcc
	v_cndmask_b32_e32 v139, v24, v25, vcc
	v_mov_b32_dpp v140, v136 quad_perm:[1,0,3,2] row_mask:0xf bank_mask:0xf
	v_mov_b32_dpp v141, v137 quad_perm:[1,0,3,2] row_mask:0xf bank_mask:0xf
	v_mov_b32_dpp v142, v138 quad_perm:[1,0,3,2] row_mask:0xf bank_mask:0xf
	v_mov_b32_dpp v143, v139 quad_perm:[1,0,3,2] row_mask:0xf bank_mask:0xf
	v_cndmask_b32_e32 v144, v140, v6, vcc
	v_cndmask_b32_e32 v248, v7, v140, vcc
	v_cndmask_b32_e32 v225, v141, v8, vcc
	v_cndmask_b32_e32 v249, v9, v141, vcc
	v_cndmask_b32_e32 v242, v142, v22, vcc
	v_cndmask_b32_e32 v250, v23, v142, vcc
	v_cndmask_b32_e32 v243, v143, v24, vcc
	v_cndmask_b32_e32 v251, v25, v143, vcc
	v_cvt_pk_bf16_f32 v136, v144, v248
	v_cvt_pk_bf16_f32 v137, v225, v249
	v_cvt_pk_bf16_f32 v138, v242, v250
	v_cvt_pk_bf16_f32 v139, v243, v251
	ds_write_b32 v3, v136 offset:16992
	ds_write_b32 v3, v137 offset:18048
	ds_write_b32 v3, v138 offset:25440
	ds_write_b32 v3, v139 offset:26496
	v_cndmask_b32_e32 v136, v10, v11, vcc
	v_cndmask_b32_e32 v137, v12, v13, vcc
	v_cndmask_b32_e32 v138, v26, v27, vcc
	v_cndmask_b32_e32 v139, v28, v29, vcc
	v_mov_b32_dpp v140, v136 quad_perm:[1,0,3,2] row_mask:0xf bank_mask:0xf
	v_mov_b32_dpp v141, v137 quad_perm:[1,0,3,2] row_mask:0xf bank_mask:0xf
	v_mov_b32_dpp v142, v138 quad_perm:[1,0,3,2] row_mask:0xf bank_mask:0xf
	v_mov_b32_dpp v143, v139 quad_perm:[1,0,3,2] row_mask:0xf bank_mask:0xf
	v_cndmask_b32_e32 v144, v140, v10, vcc
	v_cndmask_b32_e32 v248, v11, v140, vcc
	v_cndmask_b32_e32 v225, v141, v12, vcc
	v_cndmask_b32_e32 v249, v13, v141, vcc
	v_cndmask_b32_e32 v242, v142, v26, vcc
	v_cndmask_b32_e32 v250, v27, v142, vcc
	v_cndmask_b32_e32 v243, v143, v28, vcc
	v_cndmask_b32_e32 v251, v29, v143, vcc
	v_cvt_pk_bf16_f32 v136, v144, v248
	v_cvt_pk_bf16_f32 v137, v225, v249
	v_cvt_pk_bf16_f32 v138, v242, v250
	v_cvt_pk_bf16_f32 v139, v243, v251
	ds_write_b32 v3, v136 offset:33888
	ds_write_b32 v3, v137 offset:34944
	ds_write_b32 v3, v138 offset:42336
	ds_write_b32 v3, v139 offset:43392
	v_cndmask_b32_e32 v136, v18, v19, vcc
	v_cndmask_b32_e32 v137, v20, v21, vcc
	v_cndmask_b32_e32 v138, v30, v31, vcc
	v_cndmask_b32_e32 v139, v32, v33, vcc
	v_mov_b32_dpp v140, v136 quad_perm:[1,0,3,2] row_mask:0xf bank_mask:0xf
	v_mov_b32_dpp v141, v137 quad_perm:[1,0,3,2] row_mask:0xf bank_mask:0xf
	v_mov_b32_dpp v142, v138 quad_perm:[1,0,3,2] row_mask:0xf bank_mask:0xf
	v_mov_b32_dpp v143, v139 quad_perm:[1,0,3,2] row_mask:0xf bank_mask:0xf
	v_cndmask_b32_e32 v144, v140, v18, vcc
	v_cndmask_b32_e32 v248, v19, v140, vcc
	v_cndmask_b32_e32 v225, v141, v20, vcc
	v_cndmask_b32_e32 v249, v21, v141, vcc
	v_cndmask_b32_e32 v242, v142, v30, vcc
	v_cndmask_b32_e32 v250, v31, v142, vcc
	v_cndmask_b32_e32 v243, v143, v32, vcc
	v_cndmask_b32_e32 v251, v33, v143, vcc
	v_cvt_pk_bf16_f32 v136, v144, v248
	v_cvt_pk_bf16_f32 v137, v225, v249
	v_cvt_pk_bf16_f32 v138, v242, v250
	v_cvt_pk_bf16_f32 v139, v243, v251
	ds_write_b32 v3, v136 offset:50784
	ds_write_b32 v3, v137 offset:51840
	ds_write_b32 v3, v138 offset:59232
	ds_write_b32 v3, v139 offset:60288
	s_waitcnt lgkmcnt(0)
	s_barrier
; DI u16 f2bf(float a) { return (u16)(pack2bf(a, 0.f) & 0xffffu); }
; DI void phase_g1(const Params& p, int layer, unsigned char* smem) {
;     ...
;     } else if (kind == 2) {
; #pragma unroll
;       for (int mi = 0; mi < 4; ++mi) {
;         int b = mrow[mi] / TP, t = mrow[mi] - b * TP;
; #pragma unroll
;         for (int ni = 0; ni < 8; ++ni)
; #pragma unroll
;           for (int r = 0; r < 4; ++r) {
;             int row = col0 + wn * 128 + ni * 16 + lg * 4 + r;
;             dst[((size_t)(b * vrows + row)) * TP + t] = f2bf(acc[ni][mi][r]);
;           }
;       }
	v_and_b32_e32 v2, 31, v166
	v_lshrrev_b32_e32 v3, 5, v166
	v_lshl_add_u32 v4, v2, 3, v5
	v_mul_u32_u24_e32 v136, 0x210, v3
	v_mul_hi_i32 v138, v4, s81
	v_lshl_add_u32 v136, v2, 4, v136
	v_lshrrev_b32_e32 v139, 31, v138
	v_ashrrev_i32_e32 v138, 10, v138
	v_add_u32_e32 v137, 0x10800, v136
	v_add_u32_e32 v139, v138, v139
	v_add_u32_e32 v142, s48, v3
	v_mad_i32_i24 v138, v139, s82, v4
	v_mad_i32_i24 v143, s49, v139, v142
	v_ashrrev_i32_e32 v139, 31, v138
	s_movk_i32 s4, 0x2100
	v_lshl_add_u64 v[138:139], v[138:139], 1, s[54:55]
	ds_read_b128 v[6:9], v136
	ds_read_b128 v[10:13], v136 offset:8448
	ds_read_b128 v[14:17], v136 offset:16896
	ds_read_b128 v[18:21], v136 offset:25344
	ds_read_b128 v[22:25], v136 offset:33792
	ds_read_b128 v[26:29], v136 offset:42240
	ds_read_b128 v[30:33], v136 offset:50688
	ds_read_b128 v[34:37], v136 offset:59136
	ds_read_b128 v[38:41], v137
	ds_read_b128 v[42:45], v137 offset:8448
	ds_read_b128 v[46:49], v137 offset:16896
	ds_read_b128 v[50:53], v137 offset:25344
	ds_read_b128 v[54:57], v137 offset:33792
	ds_read_b128 v[58:61], v137 offset:42240
	ds_read_b128 v[62:65], v137 offset:50688
	ds_read_b128 v[66:69], v137 offset:59136
	s_nop 0
	v_mad_i64_i32 v[70:71], s[2:3], v143, s4, v[138:139]
	v_add_co_u32_e32 v72, vcc, 0x21000, v70
	s_nop 1
	v_addc_co_u32_e32 v73, vcc, 0, v71, vcc
	v_add_co_u32_e32 v74, vcc, 0x21000, v72
	s_nop 1
	v_addc_co_u32_e32 v75, vcc, 0, v73, vcc
	v_add_co_u32_e32 v76, vcc, 0x21000, v74
	s_nop 1
	v_addc_co_u32_e32 v77, vcc, 0, v75, vcc
	v_add_co_u32_e32 v78, vcc, 0x21000, v76
	s_nop 1
	v_addc_co_u32_e32 v79, vcc, 0, v77, vcc
	v_add_co_u32_e32 v80, vcc, 0x21000, v78
	s_nop 1
	v_addc_co_u32_e32 v81, vcc, 0, v79, vcc
	v_add_co_u32_e32 v82, vcc, 0x21000, v80
	s_nop 1
	v_addc_co_u32_e32 v83, vcc, 0, v81, vcc
	v_add_co_u32_e32 v84, vcc, 0x21000, v82
	s_nop 1
	v_addc_co_u32_e32 v85, vcc, 0, v83, vcc
	v_add_co_u32_e32 v86, vcc, 0x21000, v84
	s_nop 1
	v_addc_co_u32_e32 v87, vcc, 0, v85, vcc
	v_add_co_u32_e32 v88, vcc, 0x21000, v86
	s_nop 1
	v_addc_co_u32_e32 v89, vcc, 0, v87, vcc
	v_add_co_u32_e32 v90, vcc, 0x21000, v88
	s_nop 1
	v_addc_co_u32_e32 v91, vcc, 0, v89, vcc
	v_add_co_u32_e32 v92, vcc, 0x21000, v90
	s_nop 1
	v_addc_co_u32_e32 v93, vcc, 0, v91, vcc
	v_add_co_u32_e32 v94, vcc, 0x21000, v92
	s_nop 1
	v_addc_co_u32_e32 v95, vcc, 0, v93, vcc
	v_add_co_u32_e32 v96, vcc, 0x21000, v94
	s_nop 1
	v_addc_co_u32_e32 v97, vcc, 0, v95, vcc
	v_add_co_u32_e32 v98, vcc, 0x21000, v96
	s_nop 1
	v_addc_co_u32_e32 v99, vcc, 0, v97, vcc
	v_add_co_u32_e32 v100, vcc, 0x21000, v98
	s_nop 1
	v_addc_co_u32_e32 v101, vcc, 0, v99, vcc
	s_waitcnt lgkmcnt(0)
	s_barrier
	global_store_dwordx4 v[70:71], v[6:9], off
	global_store_dwordx4 v[72:73], v[10:13], off
	global_store_dwordx4 v[74:75], v[14:17], off
	global_store_dwordx4 v[76:77], v[18:21], off
	global_store_dwordx4 v[78:79], v[22:25], off
	global_store_dwordx4 v[80:81], v[26:29], off
	global_store_dwordx4 v[82:83], v[30:33], off
	global_store_dwordx4 v[84:85], v[34:37], off
	global_store_dwordx4 v[86:87], v[38:41], off
	global_store_dwordx4 v[88:89], v[42:45], off
	global_store_dwordx4 v[90:91], v[46:49], off
	global_store_dwordx4 v[92:93], v[50:53], off
	global_store_dwordx4 v[94:95], v[54:57], off
	global_store_dwordx4 v[96:97], v[58:61], off
	global_store_dwordx4 v[98:99], v[62:65], off
	global_store_dwordx4 v[100:101], v[66:69], off
